# full stack: srcC=0 first K-tile, no final prefetch, vectorized combine, acquire overlap, LDS-transposed attention epilogues, no s_setprio in GEMM loops, static priority for waves 4-7 in attention
# speedup vs baseline: 1.0086x; 1.0047x over previous
.LBB0_198:
	v_readlane_b32 s32, v255, 9
	s_cmp_ge_u32 s32, 4
	s_cbranch_scc0 .Lattp_0
	s_setprio 1

.LBB0_232:
	s_setprio 0
	s_waitcnt vmcnt(0) lgkmcnt(0)
	s_barrier
	s_waitcnt vmcnt(0)
	v_readlane_b32 s0, v255, 10
	v_readlane_b32 s1, v255, 11
	v_readlane_b32 s88, v255, 22
	v_readlane_b32 s92, v255, 24
	s_and_b64 vcc, exec, s[0:1]
	v_readlane_b32 s89, v255, 23
	v_readlane_b32 s93, v255, 25
	v_readlane_b32 s94, v255, 26
	v_readlane_b32 s95, v255, 27
	s_waitcnt vmcnt(0) lgkmcnt(0)
	s_barrier
	s_cbranch_vccnz .LBB0_179
	v_mbcnt_lo_u32_b32 v0, -1, 0
	v_mbcnt_hi_u32_b32 v0, -1, v0
	s_nop 0
	v_cmp_eq_u32_e32 vcc, 0, v0
	s_and_saveexec_b64 s[4:5], vcc
	s_cbranch_execz .LBB0_178
	s_mul_i32 s1, s62, 0x220
	v_readlane_b32 s2, v255, 12
	s_mul_hi_i32 s0, s62, 0x220
	s_add_u32 s6, s2, s1
	v_readlane_b32 s1, v255, 13
	s_addc_u32 s7, s1, s0
	s_mov_b32 s0, s86
	v_readlane_b32 s1, v255, 19
	s_lshl_b32 s56, s0, 3
	s_waitcnt vmcnt(0) expcnt(0) lgkmcnt(0)
	v_mov_b32_e32 v0, s1
	s_lshl_b64 s[0:1], s[56:57], 2
	s_add_u32 s0, s6, s0
	s_addc_u32 s1, s7, s1
	v_mov_b64_e32 v[2:3], s[0:1]
	ds_read_b32 v0, v0
	flat_atomic_add v2, v[2:3], v201 sc0
	s_waitcnt vmcnt(0) lgkmcnt(0)
	v_add_u32_e32 v2, 1, v2
	v_cmp_eq_u32_e32 vcc, v2, v0
	s_and_b64 exec, exec, vcc
	s_cbranch_execz .LBB0_178
	buffer_wbl2 sc1
	s_waitcnt vmcnt(0)
	v_mov_b64_e32 v[2:3], s[6:7]
	flat_atomic_add v[2:3], v201 offset:512
	s_branch .LBB0_178

.LBB0_283:
	s_setprio 0
	s_waitcnt vmcnt(0) lgkmcnt(0)
	s_barrier
	s_waitcnt vmcnt(0)
	v_readlane_b32 s0, v255, 10
	v_readlane_b32 s1, v255, 11
	s_and_b64 vcc, exec, s[0:1]
	s_waitcnt vmcnt(0) lgkmcnt(0)
	s_barrier
	s_cbranch_vccnz .LBB0_240
	v_mbcnt_lo_u32_b32 v0, -1, 0
	v_mbcnt_hi_u32_b32 v0, -1, v0
	s_nop 0
	v_cmp_eq_u32_e32 vcc, 0, v0
	s_and_saveexec_b64 s[4:5], vcc
	s_cbranch_execz .LBB0_239
	s_mul_i32 s1, s63, 0x220
	v_readlane_b32 s2, v255, 12
	s_mul_hi_i32 s0, s63, 0x220
	s_add_u32 s6, s2, s1
	v_readlane_b32 s1, v255, 13
	s_addc_u32 s7, s1, s0
	s_mov_b32 s0, s86
	v_readlane_b32 s1, v255, 19
	s_lshl_b32 s56, s0, 3
	s_waitcnt vmcnt(0) expcnt(0) lgkmcnt(0)
	v_mov_b32_e32 v0, s1
	s_lshl_b64 s[0:1], s[56:57], 2
	s_add_u32 s0, s6, s0
	s_addc_u32 s1, s7, s1
	v_mov_b64_e32 v[2:3], s[0:1]
	ds_read_b32 v0, v0
	flat_atomic_add v2, v[2:3], v201 sc0
	s_waitcnt vmcnt(0) lgkmcnt(0)
	v_add_u32_e32 v2, 1, v2
	v_cmp_eq_u32_e32 vcc, v2, v0
	s_and_b64 exec, exec, vcc
	s_cbranch_execz .LBB0_239
	buffer_wbl2 sc1
	s_waitcnt vmcnt(0)
	v_mov_b64_e32 v[2:3], s[6:7]
	flat_atomic_add v[2:3], v201 offset:512
	s_branch .LBB0_239

.LBB0_328:
	s_setprio 0
	s_waitcnt vmcnt(0) lgkmcnt(0)
	s_lshl_b32 s0, s23, 3
	s_add_i32 s0, s0, s20
	s_cmpk_gt_i32 s0, 0x7fff
	s_barrier
	s_cbranch_scc1 .LBB0_331
	s_lshl_b32 s1, s21, 3
	s_add_u32 s4, s12, 0x37e00000
	s_addc_u32 s5, s13, 0
	s_add_u32 s2, s12, 0x3de00000
	s_addc_u32 s3, s13, 0
	s_add_u32 s6, s12, 0x38e00000
	s_addc_u32 s7, s13, 0
	s_add_u32 s12, s12, 0x39e00000
	s_addc_u32 s13, s13, 0
	s_and_b32 s14, s20, 7
	s_lshl_b32 s56, s14, 7
	s_lshl_b32 s15, s14, 8
	v_lshlrev_b32_e32 v2, 1, v128
	s_add_u32 s10, s10, s15
	v_ashrrev_i32_e32 v3, 31, v2
	v_ashrrev_i32_e32 v129, 31, v128
	s_addc_u32 s11, s11, 0
	v_lshl_add_u64 v[2:3], v[2:3], 0, s[56:57]
	v_lshl_add_u64 v[4:5], v[128:129], 2, s[10:11]
	s_lshl_b32 s14, s14, 2
	s_cmpk_lg_u32 s1, 0x800
	s_cbranch_scc1 .LBB0_330
	s_sub_u32 s10, s10, s15
	s_subb_u32 s11, s11, 0
	s_and_b32 vcc_lo, s0, 1
	s_lshl_b32 vcc_hi, vcc_lo, 10
	s_lshl_b32 vcc_lo, vcc_lo, 4
	v_lshrrev_b32_e32 v2, 4, v128
	v_lshlrev_b32_e32 v2, 2, v2
	v_lshlrev_b32_e32 v4, 4, v128
	v_mov_b32_e32 v5, 0
	s_lshr_b32 s15, s0, 1
	s_add_u32 s15, s15, s22
	s_lshl_b32 s16, s15, 5
	s_add_u32 s16, s2, s16
	s_addc_u32 s17, s3, 0
	s_add_u32 s16, s16, vcc_lo
	s_addc_u32 s17, s17, 0
	global_load_dword v16, v2, s[16:17]
	s_add_u32 s16, s16, 0x40000
	s_addc_u32 s17, s17, 0
	global_load_dword v17, v2, s[16:17]
	s_add_u32 s16, s16, 0x40000
	s_addc_u32 s17, s17, 0
	global_load_dword v18, v2, s[16:17]
	s_lshl_b32 s16, s15, 11
	s_add_u32 s16, s4, s16
	s_addc_u32 s17, s5, 0
	s_add_u32 s16, s16, vcc_hi
	s_addc_u32 s17, s17, 0
	global_load_dwordx4 v[20:23], v4, s[16:17]
	s_lshl_b32 s16, s15, 11
	s_add_u32 s16, s6, s16
	s_addc_u32 s17, s7, 0
	s_add_u32 s16, s16, vcc_hi
	s_addc_u32 s17, s17, 0
	global_load_dwordx4 v[24:27], v4, s[16:17]
	s_lshl_b32 s16, s15, 11
	s_add_u32 s16, s12, s16
	s_addc_u32 s17, s13, 0
	s_add_u32 s16, s16, vcc_hi
	s_addc_u32 s17, s17, 0
	global_load_dwordx4 v[28:31], v4, s[16:17]
	s_lshl_b32 s16, s15, 12
	s_add_u32 s16, s10, s16
	s_addc_u32 s17, s11, 0
	s_add_u32 s16, s16, vcc_hi
	s_addc_u32 s17, s17, 0
	v_lshl_add_u64 v[32:33], s[16:17], 0, v[4:5]
	s_add_u32 s0, s0, s1
	s_lshr_b32 s15, s0, 1
	s_add_u32 s15, s15, s22
	s_lshl_b32 s16, s15, 5
	s_add_u32 s16, s2, s16
	s_addc_u32 s17, s3, 0
	s_add_u32 s16, s16, vcc_lo
	s_addc_u32 s17, s17, 0
	global_load_dword v36, v2, s[16:17]
	s_add_u32 s16, s16, 0x40000
	s_addc_u32 s17, s17, 0
	global_load_dword v37, v2, s[16:17]
	s_add_u32 s16, s16, 0x40000
	s_addc_u32 s17, s17, 0
	global_load_dword v38, v2, s[16:17]
	s_lshl_b32 s16, s15, 11
	s_add_u32 s16, s4, s16
	s_addc_u32 s17, s5, 0
	s_add_u32 s16, s16, vcc_hi
	s_addc_u32 s17, s17, 0
	global_load_dwordx4 v[40:43], v4, s[16:17]
	s_lshl_b32 s16, s15, 11
	s_add_u32 s16, s6, s16
	s_addc_u32 s17, s7, 0
	s_add_u32 s16, s16, vcc_hi
	s_addc_u32 s17, s17, 0
	global_load_dwordx4 v[44:47], v4, s[16:17]
	s_lshl_b32 s16, s15, 11
	s_add_u32 s16, s12, s16
	s_addc_u32 s17, s13, 0
	s_add_u32 s16, s16, vcc_hi
	s_addc_u32 s17, s17, 0
	global_load_dwordx4 v[48:51], v4, s[16:17]
	s_lshl_b32 s16, s15, 12
	s_add_u32 s16, s10, s16
	s_addc_u32 s17, s11, 0
	s_add_u32 s16, s16, vcc_hi
	s_addc_u32 s17, s17, 0
	v_lshl_add_u64 v[52:53], s[16:17], 0, v[4:5]
	s_add_u32 s0, s0, s1
	s_lshr_b32 s15, s0, 1
	s_add_u32 s15, s15, s22
	s_lshl_b32 s16, s15, 5
	s_add_u32 s16, s2, s16
	s_addc_u32 s17, s3, 0
	s_add_u32 s16, s16, vcc_lo
	s_addc_u32 s17, s17, 0
	global_load_dword v56, v2, s[16:17]
	s_add_u32 s16, s16, 0x40000
	s_addc_u32 s17, s17, 0
	global_load_dword v57, v2, s[16:17]
	s_add_u32 s16, s16, 0x40000
	s_addc_u32 s17, s17, 0
	global_load_dword v58, v2, s[16:17]
	s_lshl_b32 s16, s15, 11
	s_add_u32 s16, s4, s16
	s_addc_u32 s17, s5, 0
	s_add_u32 s16, s16, vcc_hi
	s_addc_u32 s17, s17, 0
	global_load_dwordx4 v[60:63], v4, s[16:17]
	s_lshl_b32 s16, s15, 11
	s_add_u32 s16, s6, s16
	s_addc_u32 s17, s7, 0
	s_add_u32 s16, s16, vcc_hi
	s_addc_u32 s17, s17, 0
	global_load_dwordx4 v[64:67], v4, s[16:17]
	s_lshl_b32 s16, s15, 11
	s_add_u32 s16, s12, s16
	s_addc_u32 s17, s13, 0
	s_add_u32 s16, s16, vcc_hi
	s_addc_u32 s17, s17, 0
	global_load_dwordx4 v[68:71], v4, s[16:17]
	s_lshl_b32 s16, s15, 12
	s_add_u32 s16, s10, s16
	s_addc_u32 s17, s11, 0
	s_add_u32 s16, s16, vcc_hi
	s_addc_u32 s17, s17, 0
	v_lshl_add_u64 v[72:73], s[16:17], 0, v[4:5]
	s_add_u32 s0, s0, s1
	s_lshr_b32 s15, s0, 1
	s_add_u32 s15, s15, s22
	s_lshl_b32 s16, s15, 5
	s_add_u32 s16, s2, s16
	s_addc_u32 s17, s3, 0
	s_add_u32 s16, s16, vcc_lo
	s_addc_u32 s17, s17, 0
	global_load_dword v76, v2, s[16:17]
	s_add_u32 s16, s16, 0x40000
	s_addc_u32 s17, s17, 0
	global_load_dword v77, v2, s[16:17]
	s_add_u32 s16, s16, 0x40000
	s_addc_u32 s17, s17, 0
	global_load_dword v78, v2, s[16:17]
	s_lshl_b32 s16, s15, 11
	s_add_u32 s16, s4, s16
	s_addc_u32 s17, s5, 0
	s_add_u32 s16, s16, vcc_hi
	s_addc_u32 s17, s17, 0
	global_load_dwordx4 v[80:83], v4, s[16:17]
	s_lshl_b32 s16, s15, 11
	s_add_u32 s16, s6, s16
	s_addc_u32 s17, s7, 0
	s_add_u32 s16, s16, vcc_hi
	s_addc_u32 s17, s17, 0
	global_load_dwordx4 v[84:87], v4, s[16:17]
	s_lshl_b32 s16, s15, 11
	s_add_u32 s16, s12, s16
	s_addc_u32 s17, s13, 0
	s_add_u32 s16, s16, vcc_hi
	s_addc_u32 s17, s17, 0
	global_load_dwordx4 v[88:91], v4, s[16:17]
	s_lshl_b32 s16, s15, 12
	s_add_u32 s16, s10, s16
	s_addc_u32 s17, s11, 0
	s_add_u32 s16, s16, vcc_hi
	s_addc_u32 s17, s17, 0
	v_lshl_add_u64 v[92:93], s[16:17], 0, v[4:5]
	s_add_u32 s0, s0, s1
	s_waitcnt vmcnt(18)
	v_max3_f32 v9, v16, v17, v18
	v_sub_f32_e32 v0, v16, v9
	v_exp_f32_e32 v6, v0
	v_sub_f32_e32 v0, v17, v9
	v_exp_f32_e32 v7, v0
	v_sub_f32_e32 v0, v18, v9
	v_exp_f32_e32 v8, v0
	v_add_f32_e32 v0, v6, v7
	v_add_f32_e32 v0, v8, v0
	v_div_scale_f32 v9, s[16:17], v0, v0, 1.0
	v_rcp_f32_e32 v10, v9
	s_nop 0
	v_fma_f32 v11, -v9, v10, 1.0
	v_fmac_f32_e32 v10, v11, v10
	v_div_scale_f32 v11, vcc, 1.0, v0, 1.0
	v_mul_f32_e32 v12, v11, v10
	v_fma_f32 v13, -v9, v12, v11
	v_fmac_f32_e32 v12, v13, v10
	v_fma_f32 v9, -v9, v12, v11
	v_div_fmas_f32 v9, v9, v10, v12
	v_div_fixup_f32 v0, v9, v0, 1.0
	v_mul_f32_e32 v6, v6, v0
	v_mul_f32_e32 v7, v7, v0
	v_mul_f32_e32 v8, v8, v0
	v_cvt_f32_f16_e32 v10, v24
	v_cvt_f32_f16_e32 v11, v20
	v_cvt_f32_f16_e32 v12, v28
	v_mul_f32_e32 v10, v7, v10
	v_fma_f32 v10, v6, v11, v10
	v_fma_f32 v10, v8, v12, v10
	v_cvt_f32_f16_sdwa v11, v20 dst_sel:DWORD dst_unused:UNUSED_PAD src0_sel:WORD_1
	v_cvt_f32_f16_sdwa v12, v24 dst_sel:DWORD dst_unused:UNUSED_PAD src0_sel:WORD_1
	v_cvt_f32_f16_sdwa v13, v28 dst_sel:DWORD dst_unused:UNUSED_PAD src0_sel:WORD_1
	v_mul_f32_e32 v11, v6, v11
	v_fma_f32 v11, v7, v12, v11
	v_fma_f32 v11, v8, v13, v11
	v_cvt_pk_bf16_f32 v20, v10, v11
	v_cvt_f32_f16_e32 v10, v25
	v_cvt_f32_f16_e32 v11, v21
	v_cvt_f32_f16_e32 v12, v29
	v_mul_f32_e32 v10, v7, v10
	v_fma_f32 v10, v6, v11, v10
	v_fma_f32 v10, v8, v12, v10
	v_cvt_f32_f16_sdwa v11, v21 dst_sel:DWORD dst_unused:UNUSED_PAD src0_sel:WORD_1
	v_cvt_f32_f16_sdwa v12, v25 dst_sel:DWORD dst_unused:UNUSED_PAD src0_sel:WORD_1
	v_cvt_f32_f16_sdwa v13, v29 dst_sel:DWORD dst_unused:UNUSED_PAD src0_sel:WORD_1
	v_mul_f32_e32 v11, v6, v11
	v_fma_f32 v11, v7, v12, v11
	v_fma_f32 v11, v8, v13, v11
	v_cvt_pk_bf16_f32 v21, v10, v11
	v_cvt_f32_f16_e32 v10, v26
	v_cvt_f32_f16_e32 v11, v22
	v_cvt_f32_f16_e32 v12, v30
	v_mul_f32_e32 v10, v7, v10
	v_fma_f32 v10, v6, v11, v10
	v_fma_f32 v10, v8, v12, v10
	v_cvt_f32_f16_sdwa v11, v22 dst_sel:DWORD dst_unused:UNUSED_PAD src0_sel:WORD_1
	v_cvt_f32_f16_sdwa v12, v26 dst_sel:DWORD dst_unused:UNUSED_PAD src0_sel:WORD_1
	v_cvt_f32_f16_sdwa v13, v30 dst_sel:DWORD dst_unused:UNUSED_PAD src0_sel:WORD_1
	v_mul_f32_e32 v11, v6, v11
	v_fma_f32 v11, v7, v12, v11
	v_fma_f32 v11, v8, v13, v11
	v_cvt_pk_bf16_f32 v22, v10, v11
	v_cvt_f32_f16_e32 v10, v27
	v_cvt_f32_f16_e32 v11, v23
	v_cvt_f32_f16_e32 v12, v31
	v_mul_f32_e32 v10, v7, v10
	v_fma_f32 v10, v6, v11, v10
	v_fma_f32 v10, v8, v12, v10
	v_cvt_f32_f16_sdwa v11, v23 dst_sel:DWORD dst_unused:UNUSED_PAD src0_sel:WORD_1
	v_cvt_f32_f16_sdwa v12, v27 dst_sel:DWORD dst_unused:UNUSED_PAD src0_sel:WORD_1
	v_cvt_f32_f16_sdwa v13, v31 dst_sel:DWORD dst_unused:UNUSED_PAD src0_sel:WORD_1
	v_mul_f32_e32 v11, v6, v11
	v_fma_f32 v11, v7, v12, v11
	v_fma_f32 v11, v8, v13, v11
	v_cvt_pk_bf16_f32 v23, v10, v11
	global_store_dwordx4 v[32:33], v[20:23], off
	s_waitcnt vmcnt(13)
	v_max3_f32 v9, v36, v37, v38
	v_sub_f32_e32 v0, v36, v9
	v_exp_f32_e32 v6, v0
	v_sub_f32_e32 v0, v37, v9
	v_exp_f32_e32 v7, v0
	v_sub_f32_e32 v0, v38, v9
	v_exp_f32_e32 v8, v0
	v_add_f32_e32 v0, v6, v7
	v_add_f32_e32 v0, v8, v0
	v_div_scale_f32 v9, s[16:17], v0, v0, 1.0
	v_rcp_f32_e32 v10, v9
	s_nop 0
	v_fma_f32 v11, -v9, v10, 1.0
	v_fmac_f32_e32 v10, v11, v10
	v_div_scale_f32 v11, vcc, 1.0, v0, 1.0
	v_mul_f32_e32 v12, v11, v10
	v_fma_f32 v13, -v9, v12, v11
	v_fmac_f32_e32 v12, v13, v10
	v_fma_f32 v9, -v9, v12, v11
	v_div_fmas_f32 v9, v9, v10, v12
	v_div_fixup_f32 v0, v9, v0, 1.0
	v_mul_f32_e32 v6, v6, v0
	v_mul_f32_e32 v7, v7, v0
	v_mul_f32_e32 v8, v8, v0
	v_cvt_f32_f16_e32 v10, v44
	v_cvt_f32_f16_e32 v11, v40
	v_cvt_f32_f16_e32 v12, v48
	v_mul_f32_e32 v10, v7, v10
	v_fma_f32 v10, v6, v11, v10
	v_fma_f32 v10, v8, v12, v10
	v_cvt_f32_f16_sdwa v11, v40 dst_sel:DWORD dst_unused:UNUSED_PAD src0_sel:WORD_1
	v_cvt_f32_f16_sdwa v12, v44 dst_sel:DWORD dst_unused:UNUSED_PAD src0_sel:WORD_1
	v_cvt_f32_f16_sdwa v13, v48 dst_sel:DWORD dst_unused:UNUSED_PAD src0_sel:WORD_1
	v_mul_f32_e32 v11, v6, v11
	v_fma_f32 v11, v7, v12, v11
	v_fma_f32 v11, v8, v13, v11
	v_cvt_pk_bf16_f32 v40, v10, v11
	v_cvt_f32_f16_e32 v10, v45
	v_cvt_f32_f16_e32 v11, v41
	v_cvt_f32_f16_e32 v12, v49
	v_mul_f32_e32 v10, v7, v10
	v_fma_f32 v10, v6, v11, v10
	v_fma_f32 v10, v8, v12, v10
	v_cvt_f32_f16_sdwa v11, v41 dst_sel:DWORD dst_unused:UNUSED_PAD src0_sel:WORD_1
	v_cvt_f32_f16_sdwa v12, v45 dst_sel:DWORD dst_unused:UNUSED_PAD src0_sel:WORD_1
	v_cvt_f32_f16_sdwa v13, v49 dst_sel:DWORD dst_unused:UNUSED_PAD src0_sel:WORD_1
	v_mul_f32_e32 v11, v6, v11
	v_fma_f32 v11, v7, v12, v11
	v_fma_f32 v11, v8, v13, v11
	v_cvt_pk_bf16_f32 v41, v10, v11
	v_cvt_f32_f16_e32 v10, v46
	v_cvt_f32_f16_e32 v11, v42
	v_cvt_f32_f16_e32 v12, v50
	v_mul_f32_e32 v10, v7, v10
	v_fma_f32 v10, v6, v11, v10
	v_fma_f32 v10, v8, v12, v10
	v_cvt_f32_f16_sdwa v11, v42 dst_sel:DWORD dst_unused:UNUSED_PAD src0_sel:WORD_1
	v_cvt_f32_f16_sdwa v12, v46 dst_sel:DWORD dst_unused:UNUSED_PAD src0_sel:WORD_1
	v_cvt_f32_f16_sdwa v13, v50 dst_sel:DWORD dst_unused:UNUSED_PAD src0_sel:WORD_1
	v_mul_f32_e32 v11, v6, v11
	v_fma_f32 v11, v7, v12, v11
	v_fma_f32 v11, v8, v13, v11
	v_cvt_pk_bf16_f32 v42, v10, v11
	v_cvt_f32_f16_e32 v10, v47
	v_cvt_f32_f16_e32 v11, v43
	v_cvt_f32_f16_e32 v12, v51
	v_mul_f32_e32 v10, v7, v10
	v_fma_f32 v10, v6, v11, v10
	v_fma_f32 v10, v8, v12, v10
	v_cvt_f32_f16_sdwa v11, v43 dst_sel:DWORD dst_unused:UNUSED_PAD src0_sel:WORD_1
	v_cvt_f32_f16_sdwa v12, v47 dst_sel:DWORD dst_unused:UNUSED_PAD src0_sel:WORD_1
	v_cvt_f32_f16_sdwa v13, v51 dst_sel:DWORD dst_unused:UNUSED_PAD src0_sel:WORD_1
	v_mul_f32_e32 v11, v6, v11
	v_fma_f32 v11, v7, v12, v11
	v_fma_f32 v11, v8, v13, v11
	v_cvt_pk_bf16_f32 v43, v10, v11
	global_store_dwordx4 v[52:53], v[40:43], off
	s_waitcnt vmcnt(8)
	v_max3_f32 v9, v56, v57, v58
	v_sub_f32_e32 v0, v56, v9
	v_exp_f32_e32 v6, v0
	v_sub_f32_e32 v0, v57, v9
	v_exp_f32_e32 v7, v0
	v_sub_f32_e32 v0, v58, v9
	v_exp_f32_e32 v8, v0
	v_add_f32_e32 v0, v6, v7
	v_add_f32_e32 v0, v8, v0
	v_div_scale_f32 v9, s[16:17], v0, v0, 1.0
	v_rcp_f32_e32 v10, v9
	s_nop 0
	v_fma_f32 v11, -v9, v10, 1.0
	v_fmac_f32_e32 v10, v11, v10
	v_div_scale_f32 v11, vcc, 1.0, v0, 1.0
	v_mul_f32_e32 v12, v11, v10
	v_fma_f32 v13, -v9, v12, v11
	v_fmac_f32_e32 v12, v13, v10
	v_fma_f32 v9, -v9, v12, v11
	v_div_fmas_f32 v9, v9, v10, v12
	v_div_fixup_f32 v0, v9, v0, 1.0
	v_mul_f32_e32 v6, v6, v0
	v_mul_f32_e32 v7, v7, v0
	v_mul_f32_e32 v8, v8, v0
	v_cvt_f32_f16_e32 v10, v64
	v_cvt_f32_f16_e32 v11, v60
	v_cvt_f32_f16_e32 v12, v68
	v_mul_f32_e32 v10, v7, v10
	v_fma_f32 v10, v6, v11, v10
	v_fma_f32 v10, v8, v12, v10
	v_cvt_f32_f16_sdwa v11, v60 dst_sel:DWORD dst_unused:UNUSED_PAD src0_sel:WORD_1
	v_cvt_f32_f16_sdwa v12, v64 dst_sel:DWORD dst_unused:UNUSED_PAD src0_sel:WORD_1
	v_cvt_f32_f16_sdwa v13, v68 dst_sel:DWORD dst_unused:UNUSED_PAD src0_sel:WORD_1
	v_mul_f32_e32 v11, v6, v11
	v_fma_f32 v11, v7, v12, v11
	v_fma_f32 v11, v8, v13, v11
	v_cvt_pk_bf16_f32 v60, v10, v11
	v_cvt_f32_f16_e32 v10, v65
	v_cvt_f32_f16_e32 v11, v61
	v_cvt_f32_f16_e32 v12, v69
	v_mul_f32_e32 v10, v7, v10
	v_fma_f32 v10, v6, v11, v10
	v_fma_f32 v10, v8, v12, v10
	v_cvt_f32_f16_sdwa v11, v61 dst_sel:DWORD dst_unused:UNUSED_PAD src0_sel:WORD_1
	v_cvt_f32_f16_sdwa v12, v65 dst_sel:DWORD dst_unused:UNUSED_PAD src0_sel:WORD_1
	v_cvt_f32_f16_sdwa v13, v69 dst_sel:DWORD dst_unused:UNUSED_PAD src0_sel:WORD_1
	v_mul_f32_e32 v11, v6, v11
	v_fma_f32 v11, v7, v12, v11
	v_fma_f32 v11, v8, v13, v11
	v_cvt_pk_bf16_f32 v61, v10, v11
	v_cvt_f32_f16_e32 v10, v66
	v_cvt_f32_f16_e32 v11, v62
	v_cvt_f32_f16_e32 v12, v70
	v_mul_f32_e32 v10, v7, v10
	v_fma_f32 v10, v6, v11, v10
	v_fma_f32 v10, v8, v12, v10
	v_cvt_f32_f16_sdwa v11, v62 dst_sel:DWORD dst_unused:UNUSED_PAD src0_sel:WORD_1
	v_cvt_f32_f16_sdwa v12, v66 dst_sel:DWORD dst_unused:UNUSED_PAD src0_sel:WORD_1
	v_cvt_f32_f16_sdwa v13, v70 dst_sel:DWORD dst_unused:UNUSED_PAD src0_sel:WORD_1
	v_mul_f32_e32 v11, v6, v11
	v_fma_f32 v11, v7, v12, v11
	v_fma_f32 v11, v8, v13, v11
	v_cvt_pk_bf16_f32 v62, v10, v11
	v_cvt_f32_f16_e32 v10, v67
	v_cvt_f32_f16_e32 v11, v63
	v_cvt_f32_f16_e32 v12, v71
	v_mul_f32_e32 v10, v7, v10
	v_fma_f32 v10, v6, v11, v10
	v_fma_f32 v10, v8, v12, v10
	v_cvt_f32_f16_sdwa v11, v63 dst_sel:DWORD dst_unused:UNUSED_PAD src0_sel:WORD_1
	v_cvt_f32_f16_sdwa v12, v67 dst_sel:DWORD dst_unused:UNUSED_PAD src0_sel:WORD_1
	v_cvt_f32_f16_sdwa v13, v71 dst_sel:DWORD dst_unused:UNUSED_PAD src0_sel:WORD_1
	v_mul_f32_e32 v11, v6, v11
	v_fma_f32 v11, v7, v12, v11
	v_fma_f32 v11, v8, v13, v11
	v_cvt_pk_bf16_f32 v63, v10, v11
	global_store_dwordx4 v[72:73], v[60:63], off
	s_waitcnt vmcnt(3)
	v_max3_f32 v9, v76, v77, v78
	v_sub_f32_e32 v0, v76, v9
	v_exp_f32_e32 v6, v0
	v_sub_f32_e32 v0, v77, v9
	v_exp_f32_e32 v7, v0
	v_sub_f32_e32 v0, v78, v9
	v_exp_f32_e32 v8, v0
	v_add_f32_e32 v0, v6, v7
	v_add_f32_e32 v0, v8, v0
	v_div_scale_f32 v9, s[16:17], v0, v0, 1.0
	v_rcp_f32_e32 v10, v9
	s_nop 0
	v_fma_f32 v11, -v9, v10, 1.0
	v_fmac_f32_e32 v10, v11, v10
	v_div_scale_f32 v11, vcc, 1.0, v0, 1.0
	v_mul_f32_e32 v12, v11, v10
	v_fma_f32 v13, -v9, v12, v11
	v_fmac_f32_e32 v12, v13, v10
	v_fma_f32 v9, -v9, v12, v11
	v_div_fmas_f32 v9, v9, v10, v12
	v_div_fixup_f32 v0, v9, v0, 1.0
	v_mul_f32_e32 v6, v6, v0
	v_mul_f32_e32 v7, v7, v0
	v_mul_f32_e32 v8, v8, v0
	v_cvt_f32_f16_e32 v10, v84
	v_cvt_f32_f16_e32 v11, v80
	v_cvt_f32_f16_e32 v12, v88
	v_mul_f32_e32 v10, v7, v10
	v_fma_f32 v10, v6, v11, v10
	v_fma_f32 v10, v8, v12, v10
	v_cvt_f32_f16_sdwa v11, v80 dst_sel:DWORD dst_unused:UNUSED_PAD src0_sel:WORD_1
	v_cvt_f32_f16_sdwa v12, v84 dst_sel:DWORD dst_unused:UNUSED_PAD src0_sel:WORD_1
	v_cvt_f32_f16_sdwa v13, v88 dst_sel:DWORD dst_unused:UNUSED_PAD src0_sel:WORD_1
	v_mul_f32_e32 v11, v6, v11
	v_fma_f32 v11, v7, v12, v11
	v_fma_f32 v11, v8, v13, v11
	v_cvt_pk_bf16_f32 v80, v10, v11
	v_cvt_f32_f16_e32 v10, v85
	v_cvt_f32_f16_e32 v11, v81
	v_cvt_f32_f16_e32 v12, v89
	v_mul_f32_e32 v10, v7, v10
	v_fma_f32 v10, v6, v11, v10
	v_fma_f32 v10, v8, v12, v10
	v_cvt_f32_f16_sdwa v11, v81 dst_sel:DWORD dst_unused:UNUSED_PAD src0_sel:WORD_1
	v_cvt_f32_f16_sdwa v12, v85 dst_sel:DWORD dst_unused:UNUSED_PAD src0_sel:WORD_1
	v_cvt_f32_f16_sdwa v13, v89 dst_sel:DWORD dst_unused:UNUSED_PAD src0_sel:WORD_1
	v_mul_f32_e32 v11, v6, v11
	v_fma_f32 v11, v7, v12, v11
	v_fma_f32 v11, v8, v13, v11
	v_cvt_pk_bf16_f32 v81, v10, v11
	v_cvt_f32_f16_e32 v10, v86
	v_cvt_f32_f16_e32 v11, v82
	v_cvt_f32_f16_e32 v12, v90
	v_mul_f32_e32 v10, v7, v10
	v_fma_f32 v10, v6, v11, v10
	v_fma_f32 v10, v8, v12, v10
	v_cvt_f32_f16_sdwa v11, v82 dst_sel:DWORD dst_unused:UNUSED_PAD src0_sel:WORD_1
	v_cvt_f32_f16_sdwa v12, v86 dst_sel:DWORD dst_unused:UNUSED_PAD src0_sel:WORD_1
	v_cvt_f32_f16_sdwa v13, v90 dst_sel:DWORD dst_unused:UNUSED_PAD src0_sel:WORD_1
	v_mul_f32_e32 v11, v6, v11
	v_fma_f32 v11, v7, v12, v11
	v_fma_f32 v11, v8, v13, v11
	v_cvt_pk_bf16_f32 v82, v10, v11
	v_cvt_f32_f16_e32 v10, v87
	v_cvt_f32_f16_e32 v11, v83
	v_cvt_f32_f16_e32 v12, v91
	v_mul_f32_e32 v10, v7, v10
	v_fma_f32 v10, v6, v11, v10
	v_fma_f32 v10, v8, v12, v10
	v_cvt_f32_f16_sdwa v11, v83 dst_sel:DWORD dst_unused:UNUSED_PAD src0_sel:WORD_1
	v_cvt_f32_f16_sdwa v12, v87 dst_sel:DWORD dst_unused:UNUSED_PAD src0_sel:WORD_1
	v_cvt_f32_f16_sdwa v13, v91 dst_sel:DWORD dst_unused:UNUSED_PAD src0_sel:WORD_1
	v_mul_f32_e32 v11, v6, v11
	v_fma_f32 v11, v7, v12, v11
	v_fma_f32 v11, v8, v13, v11
	v_cvt_pk_bf16_f32 v83, v10, v11
	global_store_dwordx4 v[92:93], v[80:83], off
	s_branch .LBB0_331
